# S5 in-projection wait leaves the previous step's y stores in flight for waves 4-7
# speedup vs baseline: 1.0139x; 1.0016x over previous
; __device__ __forceinline__ void s5_unit(const Args& A, char* lds, int b, int g) {
;     ...
;     for (int i = 0; i < SEQL / 64 + 2; ++i) {
;         if (i < SEQL / 64) { float* BU = (float*)(lds + S5_BU) + (i & 1) * (64 * 132); f32x16 acc = {};
;             acc = __builtin_amdgcn_mfma_f32_32x32x16_bf16(un, bfrag, acc, 0, 0, 0);
;             if (ntile == 0) *(bf16x8*)((bf16*)(lds + S5_US) + ((i & 3) * 64 + ttile * 32 + r32) * 16 + 8 * hi) = un;
;             if (i + 1 < SEQL / 64) un = *(const bf16x8*)(pU + (size_t)(i + 1) * 64 * LD1);
.LBB0_1348:
	s_add_i32 s45, s8, 2
	s_cmp_gt_u32 s45, 31
	s_cbranch_scc1 .LBB0_1353
	s_cmp_lt_u32 s99, 4
	s_cbranch_scc1 .Ls5_w0
	s_cmp_lt_u32 s45, 3
	s_cbranch_scc1 .Ls5_w0
	s_waitcnt vmcnt(4) lgkmcnt(0)
	s_branch .Ls5_w1
.Ls5_w0:
	s_waitcnt vmcnt(0) lgkmcnt(0)
.Ls5_w1:
	v_mfma_f32_32x32x16_bf16 v[0:15], v[36:39], v[20:23], 0
	s_andn2_b64 vcc, exec, s[20:21]
	s_cbranch_vccz .LBB0_1362
	s_cmpk_eq_i32 s44, 0x740
	s_cbranch_scc1 .LBB0_1352
